# loop-edge: K-loop scalar bookkeeping (increments + next-tile address selects) rotated from the head of the first load segment into the tail of the last MFMA segment, P2 and P5 loops
# baseline (speedup 1.0000x reference)
; #define PG8_STAGE(bufoff, gbase, voff) do { _Pragma("unroll") for (int _i = 0; _i < 2; ++_i) \
;         __builtin_amdgcn_global_load_lds((const unsigned*)((const char*)(gbase) + (voff)[_i]), (LAS unsigned*)(lds + (bufoff) + ldsw + _i * 8192), 16, 0, 0); } while (0)
; #define PG8_LDA(dst, b, h) do { _Pragma("unroll") for (int m = 0; m < 4; ++m) _Pragma("unroll") for (int k = 0; k < 2; ++k) dst[m][k] = *(const LAS bf16x8*)(lds + PG8_SA(b, h) + aoff + m * 2048 + k * 1024); } while (0)
; #define PG8_LDB(dst, b, h) do { _Pragma("unroll") for (int n = 0; n < 2; ++n) _Pragma("unroll") for (int k = 0; k < 2; ++k) dst[n][k] = *(const LAS bf16x8*)(lds + PG8_SB(b, h) + boff + n * 2048 + k * 1024); } while (0)
; #define PG8_MMA(ai, bj, At, Bt) do { __builtin_amdgcn_s_setprio(1); _Pragma("unroll") for (int m = 0; m < 4; ++m) _Pragma("unroll") for (int n = 0; n < 2; ++n) _Pragma("unroll") for (int k = 0; k < 2; ++k) \
;         acc[ai][bj][m][n] = __builtin_amdgcn_mfma_f32_16x16x32_bf16(Bt[n][k], At[m][k], acc[ai][bj][m][n], 0, 0, 0); __builtin_amdgcn_s_setprio(0); } while (0)
; #define PG8_WAIT_V(n) asm volatile("s_waitcnt vmcnt(" #n ")" ::: "memory")
; #define PG8_WAIT_L(n) asm volatile("s_waitcnt lgkmcnt(" #n ")" ::: "memory")
; #define PG8_BAR __builtin_amdgcn_s_barrier()
; #define PG8_SCHED __builtin_amdgcn_sched_barrier(0)
; template <class Epi, class Sched>
; __device__ __forceinline__ void gemm_stream(LAS unsigned char* lds, const int lda, const int ldb, const Sched& S, const Epi& E, const int wv) {
;     ...
;         for (int t = 0; t < nt; t += 2) {
;             const bool last = (t == nt - 2);
;             const char* a1 = cA + (size_t)(t + 1) * kstep;
;             const char* a2 = last ? nA : cA + (size_t)(t + 2) * kstep; const char* b2 = last ? nB : cB + (size_t)(t + 2) * kstep;
;             const char* a3 = a2 + kstep; const char* b3 = b2 + kstep;
;             PG8_LDB(B0, 0, 0); PG8_LDB(B1, 0, 1); PG8_SCHED; PG8_LDA(At, 0, 0); PG8_STAGE(PG8_SA(1, 1), a1 + hstepA, voffA);
;             PG8_WAIT_V(8); PG8_WAIT_L(0); PG8_BAR; PG8_MMA(0, 0, At, B0); PG8_MMA(0, 1, At, B1); PG8_BAR; PG8_SCHED;
;             PG8_LDA(At, 0, 1); PG8_STAGE(PG8_SB(0, 0), b2, voffB); PG8_STAGE(PG8_SB(0, 1), b2 + hstepB, voffB); PG8_STAGE(PG8_SA(0, 0), a2, voffA);
;             PG8_WAIT_V(8); PG8_WAIT_L(0); PG8_BAR; PG8_MMA(1, 0, At, B0); PG8_MMA(1, 1, At, B1); PG8_BAR; PG8_SCHED;
.Lp2_ktop:
	v_add_u32_e32 v140, s38, v163
	v_add_u32_e32 v160, s59, v163
	ds_read_b128 v[128:131], v140
	ds_read_b128 v[132:135], v140 offset:1024
	ds_read_b128 v[136:139], v140 offset:2048
	ds_read_b128 v[140:143], v140 offset:3072
	ds_read_b128 v[156:159], v160
	ds_read_b128 v[166:169], v160 offset:1024
	ds_read_b128 v[170:173], v160 offset:2048
	ds_read_b128 v[174:177], v160 offset:3072
	v_lshl_add_u64 v[160:161], s[28:29], 0, v[152:153]
	s_add_i32 m0, s42, 0xc000
	ds_read_b128 v[178:181], v164
	ds_read_b128 v[182:185], v164 offset:1024
	ds_read_b128 v[186:189], v164 offset:2048
	ds_read_b128 v[190:193], v164 offset:3072
	ds_read_b128 v[200:203], v164 offset:4096
	ds_read_b128 v[204:207], v164 offset:5120
	ds_read_b128 v[208:211], v164 offset:6144
	ds_read_b128 v[212:215], v164 offset:7168
	global_load_lds_dwordx4 v[160:161], off
	v_lshl_add_u64 v[160:161], s[28:29], 0, v[154:155]
	s_add_i32 m0, s42, 0xe000
	s_nop 0
	global_load_lds_dwordx4 v[160:161], off
	s_waitcnt vmcnt(8)
	s_waitcnt lgkmcnt(0)
	s_barrier
	s_setprio 1
	s_waitcnt lgkmcnt(0)
	v_mfma_f32_16x16x32_bf16 v[124:127], v[128:131], v[178:181], v[124:127]
	v_mfma_f32_16x16x32_bf16 v[120:123], v[136:139], v[178:181], v[120:123]
	v_mfma_f32_16x16x32_bf16 v[108:111], v[128:131], v[186:189], v[108:111]
	v_mfma_f32_16x16x32_bf16 v[104:107], v[136:139], v[186:189], v[104:107]
	v_mfma_f32_16x16x32_bf16 v[92:95], v[128:131], v[200:203], v[92:95]
	v_mfma_f32_16x16x32_bf16 v[88:91], v[136:139], v[200:203], v[88:91]
	v_mfma_f32_16x16x32_bf16 v[76:79], v[128:131], v[208:211], v[76:79]
	v_mfma_f32_16x16x32_bf16 v[72:75], v[136:139], v[208:211], v[72:75]
	v_mfma_f32_16x16x32_bf16 v[124:127], v[132:135], v[182:185], v[124:127]
	v_mfma_f32_16x16x32_bf16 v[120:123], v[140:143], v[182:185], v[120:123]
	v_mfma_f32_16x16x32_bf16 v[108:111], v[132:135], v[190:193], v[108:111]
	v_mfma_f32_16x16x32_bf16 v[104:107], v[140:143], v[190:193], v[104:107]
	v_mfma_f32_16x16x32_bf16 v[92:95], v[132:135], v[204:207], v[92:95]
	v_mfma_f32_16x16x32_bf16 v[88:91], v[140:143], v[204:207], v[88:91]
	v_mfma_f32_16x16x32_bf16 v[76:79], v[132:135], v[212:215], v[76:79]
	v_mfma_f32_16x16x32_bf16 v[72:75], v[140:143], v[212:215], v[72:75]
	s_setprio 0
	s_setprio 1
	v_mfma_f32_16x16x32_bf16 v[116:119], v[156:159], v[178:181], v[116:119]
	v_mfma_f32_16x16x32_bf16 v[112:115], v[170:173], v[178:181], v[112:115]
	v_mfma_f32_16x16x32_bf16 v[100:103], v[156:159], v[186:189], v[100:103]
	v_mfma_f32_16x16x32_bf16 v[96:99], v[170:173], v[186:189], v[96:99]
	v_mfma_f32_16x16x32_bf16 v[84:87], v[156:159], v[200:203], v[84:87]
	v_mfma_f32_16x16x32_bf16 v[80:83], v[170:173], v[200:203], v[80:83]
	v_mfma_f32_16x16x32_bf16 v[68:71], v[156:159], v[208:211], v[68:71]
	v_mfma_f32_16x16x32_bf16 v[64:67], v[170:173], v[208:211], v[64:67]
	v_mfma_f32_16x16x32_bf16 v[116:119], v[166:169], v[182:185], v[116:119]
	v_mfma_f32_16x16x32_bf16 v[112:115], v[174:177], v[182:185], v[112:115]
	v_mfma_f32_16x16x32_bf16 v[100:103], v[166:169], v[190:193], v[100:103]
	v_mfma_f32_16x16x32_bf16 v[96:99], v[174:177], v[190:193], v[96:99]
	v_mfma_f32_16x16x32_bf16 v[84:87], v[166:169], v[204:207], v[84:87]
	v_mfma_f32_16x16x32_bf16 v[80:83], v[174:177], v[204:207], v[80:83]
	v_mfma_f32_16x16x32_bf16 v[68:71], v[166:169], v[212:215], v[68:71]
	v_mfma_f32_16x16x32_bf16 v[64:67], v[174:177], v[212:215], v[64:67]
	s_setprio 0
	s_barrier
	s_add_i32 s38, s38, s41
	v_lshl_add_u64 v[160:161], s[30:31], 0, v[146:147]
	s_mov_b32 m0, s38
	ds_read_b128 v[178:181], v164 offset:16384
	ds_read_b128 v[182:185], v164 offset:17408
	ds_read_b128 v[186:189], v164 offset:18432
	ds_read_b128 v[190:193], v164 offset:19456
	ds_read_b128 v[200:203], v164 offset:20480
	ds_read_b128 v[204:207], v164 offset:21504
	ds_read_b128 v[208:211], v164 offset:22528
	ds_read_b128 v[212:215], v164 offset:23552
	global_load_lds_dwordx4 v[160:161], off
	s_add_i32 m0, s38, 0x2000
	s_add_u32 s38, s30, 0x20000
	v_lshl_add_u64 v[216:217], s[30:31], 0, v[150:151]
	s_addc_u32 s39, s31, 0
	s_add_i32 s59, s59, s41
	global_load_lds_dwordx4 v[216:217], off
	v_lshl_add_u64 v[218:219], s[38:39], 0, v[146:147]
	s_mov_b32 m0, s59
	v_lshl_add_u64 v[220:221], s[34:35], 0, v[148:149]
	global_load_lds_dwordx4 v[218:219], off
	v_lshl_add_u64 v[218:219], s[38:39], 0, v[150:151]
	s_add_i32 m0, s59, 0x2000
	s_nop 0
	global_load_lds_dwordx4 v[218:219], off
	v_lshl_add_u64 v[218:219], s[34:35], 0, v[144:145]
	s_mov_b32 m0, s42
	s_nop 0
	global_load_lds_dwordx4 v[218:219], off
	s_mov_b32 m0, s43
	s_nop 0
	global_load_lds_dwordx4 v[220:221], off
	s_waitcnt vmcnt(8)
	s_waitcnt lgkmcnt(0)
	s_barrier
; #define PG8_STAGE(bufoff, gbase, voff) do { _Pragma("unroll") for (int _i = 0; _i < 2; ++_i) \
;         __builtin_amdgcn_global_load_lds((const unsigned*)((const char*)(gbase) + (voff)[_i]), (LAS unsigned*)(lds + (bufoff) + ldsw + _i * 8192), 16, 0, 0); } while (0)
; #define PG8_LDA(dst, b, h) do { _Pragma("unroll") for (int m = 0; m < 4; ++m) _Pragma("unroll") for (int k = 0; k < 2; ++k) dst[m][k] = *(const LAS bf16x8*)(lds + PG8_SA(b, h) + aoff + m * 2048 + k * 1024); } while (0)
; #define PG8_LDB(dst, b, h) do { _Pragma("unroll") for (int n = 0; n < 2; ++n) _Pragma("unroll") for (int k = 0; k < 2; ++k) dst[n][k] = *(const LAS bf16x8*)(lds + PG8_SB(b, h) + boff + n * 2048 + k * 1024); } while (0)
; #define PG8_MMA(ai, bj, At, Bt) do { __builtin_amdgcn_s_setprio(1); _Pragma("unroll") for (int m = 0; m < 4; ++m) _Pragma("unroll") for (int n = 0; n < 2; ++n) _Pragma("unroll") for (int k = 0; k < 2; ++k) \
;         acc[ai][bj][m][n] = __builtin_amdgcn_mfma_f32_16x16x32_bf16(Bt[n][k], At[m][k], acc[ai][bj][m][n], 0, 0, 0); __builtin_amdgcn_s_setprio(0); } while (0)
; #define PG8_WAIT_V(n) asm volatile("s_waitcnt vmcnt(" #n ")" ::: "memory")
; #define PG8_WAIT_L(n) asm volatile("s_waitcnt lgkmcnt(" #n ")" ::: "memory")
; #define PG8_BAR __builtin_amdgcn_s_barrier()
; #define PG8_SCHED __builtin_amdgcn_sched_barrier(0)
; template <class Epi, class Sched>
; __device__ __forceinline__ void gemm_stream(LAS unsigned char* lds, const int lda, const int ldb, const Sched& S, const Epi& E, const int wv) {
;     ...
;             PG8_LDA(At, 0, 1); PG8_STAGE(PG8_SB(0, 0), b2, voffB); PG8_STAGE(PG8_SB(0, 1), b2 + hstepB, voffB); PG8_STAGE(PG8_SA(0, 0), a2, voffA);
;             PG8_WAIT_V(8); PG8_WAIT_L(0); PG8_BAR; PG8_MMA(1, 0, At, B0); PG8_MMA(1, 1, At, B1); PG8_BAR; PG8_SCHED;
;             PG8_LDB(B0, 1, 0); PG8_LDB(B1, 1, 1); PG8_SCHED; PG8_LDA(At, 1, 0); PG8_STAGE(PG8_SA(0, 1), a2 + hstepA, voffA);
;             PG8_WAIT_V(8); PG8_WAIT_L(0); PG8_BAR; PG8_MMA(0, 0, At, B0); PG8_MMA(0, 1, At, B1); PG8_BAR; PG8_SCHED;
	s_setprio 1
	s_waitcnt lgkmcnt(0)
	v_mfma_f32_16x16x32_bf16 v[60:63], v[128:131], v[178:181], v[60:63]
	v_mfma_f32_16x16x32_bf16 v[56:59], v[136:139], v[178:181], v[56:59]
	v_mfma_f32_16x16x32_bf16 v[44:47], v[128:131], v[186:189], v[44:47]
	v_mfma_f32_16x16x32_bf16 v[40:43], v[136:139], v[186:189], v[40:43]
	v_mfma_f32_16x16x32_bf16 v[28:31], v[128:131], v[200:203], v[28:31]
	v_mfma_f32_16x16x32_bf16 v[24:27], v[136:139], v[200:203], v[24:27]
	v_mfma_f32_16x16x32_bf16 v[12:15], v[128:131], v[208:211], v[12:15]
	v_mfma_f32_16x16x32_bf16 v[8:11], v[136:139], v[208:211], v[8:11]
	v_mfma_f32_16x16x32_bf16 v[60:63], v[132:135], v[182:185], v[60:63]
	v_mfma_f32_16x16x32_bf16 v[56:59], v[140:143], v[182:185], v[56:59]
	v_mfma_f32_16x16x32_bf16 v[44:47], v[132:135], v[190:193], v[44:47]
	v_mfma_f32_16x16x32_bf16 v[40:43], v[140:143], v[190:193], v[40:43]
	v_mfma_f32_16x16x32_bf16 v[28:31], v[132:135], v[204:207], v[28:31]
	v_mfma_f32_16x16x32_bf16 v[24:27], v[140:143], v[204:207], v[24:27]
	v_mfma_f32_16x16x32_bf16 v[12:15], v[132:135], v[212:215], v[12:15]
	v_mfma_f32_16x16x32_bf16 v[8:11], v[140:143], v[212:215], v[8:11]
	s_setprio 0
	s_setprio 1
	v_mfma_f32_16x16x32_bf16 v[52:55], v[156:159], v[178:181], v[52:55]
	v_mfma_f32_16x16x32_bf16 v[48:51], v[170:173], v[178:181], v[48:51]
	v_mfma_f32_16x16x32_bf16 v[36:39], v[156:159], v[186:189], v[36:39]
	v_mfma_f32_16x16x32_bf16 v[32:35], v[170:173], v[186:189], v[32:35]
	v_mfma_f32_16x16x32_bf16 v[20:23], v[156:159], v[200:203], v[20:23]
	v_mfma_f32_16x16x32_bf16 v[16:19], v[170:173], v[200:203], v[16:19]
	v_mfma_f32_16x16x32_bf16 v[4:7], v[156:159], v[208:211], v[4:7]
	v_mfma_f32_16x16x32_bf16 v[0:3], v[170:173], v[208:211], v[0:3]
	v_mfma_f32_16x16x32_bf16 v[52:55], v[166:169], v[182:185], v[52:55]
	v_mfma_f32_16x16x32_bf16 v[48:51], v[174:177], v[182:185], v[48:51]
	v_mfma_f32_16x16x32_bf16 v[36:39], v[166:169], v[190:193], v[36:39]
	v_mfma_f32_16x16x32_bf16 v[32:35], v[174:177], v[190:193], v[32:35]
	v_mfma_f32_16x16x32_bf16 v[20:23], v[166:169], v[204:207], v[20:23]
	v_mfma_f32_16x16x32_bf16 v[16:19], v[174:177], v[204:207], v[16:19]
	v_mfma_f32_16x16x32_bf16 v[4:7], v[166:169], v[212:215], v[4:7]
	v_mfma_f32_16x16x32_bf16 v[0:3], v[174:177], v[212:215], v[0:3]
	s_setprio 0
	s_barrier
	s_add_i32 s38, 0, 0x18000
	s_add_i32 s39, 0, 0x1c000
	v_add_u32_e32 v140, s38, v163
	v_add_u32_e32 v165, s39, v163
	ds_read_b128 v[128:131], v140
	ds_read_b128 v[132:135], v140 offset:1024
	ds_read_b128 v[136:139], v140 offset:2048
	ds_read_b128 v[140:143], v140 offset:3072
	ds_read_b128 v[156:159], v165
	ds_read_b128 v[166:169], v165 offset:1024
	ds_read_b128 v[170:173], v165 offset:2048
	ds_read_b128 v[174:177], v165 offset:3072
	s_add_u32 s34, s34, 0x80000
	s_addc_u32 s35, s35, 0
	s_mov_b32 m0, s44
	v_lshl_add_u64 v[222:223], s[34:35], 0, v[144:145]
	ds_read_b128 v[178:181], v164 offset:32768
	ds_read_b128 v[182:185], v164 offset:33792
	ds_read_b128 v[186:189], v164 offset:34816
	ds_read_b128 v[190:193], v164 offset:35840
	ds_read_b128 v[200:203], v164 offset:36864
	ds_read_b128 v[204:207], v164 offset:37888
	ds_read_b128 v[208:211], v164 offset:38912
	ds_read_b128 v[212:215], v164 offset:39936
	global_load_lds_dwordx4 v[222:223], off
	v_lshl_add_u64 v[222:223], s[34:35], 0, v[148:149]
	s_mov_b32 m0, s45
	s_nop 0
	global_load_lds_dwordx4 v[222:223], off
	s_waitcnt vmcnt(8)
	s_waitcnt lgkmcnt(0)
	s_barrier
	s_setprio 1
	s_waitcnt lgkmcnt(0)
	v_mfma_f32_16x16x32_bf16 v[124:127], v[128:131], v[178:181], v[124:127]
	v_mfma_f32_16x16x32_bf16 v[120:123], v[136:139], v[178:181], v[120:123]
	v_mfma_f32_16x16x32_bf16 v[108:111], v[128:131], v[186:189], v[108:111]
	v_mfma_f32_16x16x32_bf16 v[104:107], v[136:139], v[186:189], v[104:107]
	v_mfma_f32_16x16x32_bf16 v[92:95], v[128:131], v[200:203], v[92:95]
	v_mfma_f32_16x16x32_bf16 v[88:91], v[136:139], v[200:203], v[88:91]
	v_mfma_f32_16x16x32_bf16 v[76:79], v[128:131], v[208:211], v[76:79]
	v_mfma_f32_16x16x32_bf16 v[72:75], v[136:139], v[208:211], v[72:75]
	v_mfma_f32_16x16x32_bf16 v[124:127], v[132:135], v[182:185], v[124:127]
	v_mfma_f32_16x16x32_bf16 v[120:123], v[140:143], v[182:185], v[120:123]
	v_mfma_f32_16x16x32_bf16 v[108:111], v[132:135], v[190:193], v[108:111]
	v_mfma_f32_16x16x32_bf16 v[104:107], v[140:143], v[190:193], v[104:107]
	v_mfma_f32_16x16x32_bf16 v[92:95], v[132:135], v[204:207], v[92:95]
	v_mfma_f32_16x16x32_bf16 v[88:91], v[140:143], v[204:207], v[88:91]
	v_mfma_f32_16x16x32_bf16 v[76:79], v[132:135], v[212:215], v[76:79]
	v_mfma_f32_16x16x32_bf16 v[72:75], v[140:143], v[212:215], v[72:75]
	s_setprio 0
	s_setprio 1
	v_mfma_f32_16x16x32_bf16 v[116:119], v[156:159], v[178:181], v[116:119]
	v_mfma_f32_16x16x32_bf16 v[112:115], v[170:173], v[178:181], v[112:115]
	v_mfma_f32_16x16x32_bf16 v[100:103], v[156:159], v[186:189], v[100:103]
	v_mfma_f32_16x16x32_bf16 v[96:99], v[170:173], v[186:189], v[96:99]
	v_mfma_f32_16x16x32_bf16 v[84:87], v[156:159], v[200:203], v[84:87]
	v_mfma_f32_16x16x32_bf16 v[80:83], v[170:173], v[200:203], v[80:83]
	v_mfma_f32_16x16x32_bf16 v[68:71], v[156:159], v[208:211], v[68:71]
	v_mfma_f32_16x16x32_bf16 v[64:67], v[170:173], v[208:211], v[64:67]
	v_mfma_f32_16x16x32_bf16 v[116:119], v[166:169], v[182:185], v[116:119]
	v_mfma_f32_16x16x32_bf16 v[112:115], v[174:177], v[182:185], v[112:115]
	v_mfma_f32_16x16x32_bf16 v[100:103], v[166:169], v[190:193], v[100:103]
	v_mfma_f32_16x16x32_bf16 v[96:99], v[174:177], v[190:193], v[96:99]
	v_mfma_f32_16x16x32_bf16 v[84:87], v[166:169], v[204:207], v[84:87]
	v_mfma_f32_16x16x32_bf16 v[80:83], v[174:177], v[204:207], v[80:83]
	v_mfma_f32_16x16x32_bf16 v[68:71], v[166:169], v[212:215], v[68:71]
	v_mfma_f32_16x16x32_bf16 v[64:67], v[174:177], v[212:215], v[64:67]
	s_setprio 0
	s_barrier
; #define PG8_STAGE(bufoff, gbase, voff) do { _Pragma("unroll") for (int _i = 0; _i < 2; ++_i) \
;         __builtin_amdgcn_global_load_lds((const unsigned*)((const char*)(gbase) + (voff)[_i]), (LAS unsigned*)(lds + (bufoff) + ldsw + _i * 8192), 16, 0, 0); } while (0)
; #define PG8_LDA(dst, b, h) do { _Pragma("unroll") for (int m = 0; m < 4; ++m) _Pragma("unroll") for (int k = 0; k < 2; ++k) dst[m][k] = *(const LAS bf16x8*)(lds + PG8_SA(b, h) + aoff + m * 2048 + k * 1024); } while (0)
; #define PG8_LDB(dst, b, h) do { _Pragma("unroll") for (int n = 0; n < 2; ++n) _Pragma("unroll") for (int k = 0; k < 2; ++k) dst[n][k] = *(const LAS bf16x8*)(lds + PG8_SB(b, h) + boff + n * 2048 + k * 1024); } while (0)
; #define PG8_WAIT_V(n) asm volatile("s_waitcnt vmcnt(" #n ")" ::: "memory")
; template <class Epi, class Sched>
; __device__ __forceinline__ void gemm_stream(LAS unsigned char* lds, const int lda, const int ldb, const Sched& S, const Epi& E, const int wv) {
;     ...
;         for (int t = 0; t < nt; t += 2) {
;             const bool last = (t == nt - 2);
;             const char* a1 = cA + (size_t)(t + 1) * kstep;
;             const char* a2 = last ? nA : cA + (size_t)(t + 2) * kstep; const char* b2 = last ? nB : cB + (size_t)(t + 2) * kstep;
;             const char* a3 = a2 + kstep; const char* b3 = b2 + kstep;
;             PG8_LDB(B0, 0, 0); PG8_LDB(B1, 0, 1); PG8_SCHED; PG8_LDA(At, 0, 0); PG8_STAGE(PG8_SA(1, 1), a1 + hstepA, voffA);
;             PG8_WAIT_V(8); PG8_WAIT_L(0); PG8_BAR; PG8_MMA(0, 0, At, B0); PG8_MMA(0, 1, At, B1); PG8_BAR; PG8_SCHED;
;             PG8_LDA(At, 0, 1); PG8_STAGE(PG8_SB(0, 0), b2, voffB); PG8_STAGE(PG8_SB(0, 1), b2 + hstepB, voffB); PG8_STAGE(PG8_SA(0, 0), a2, voffA);
;             PG8_WAIT_V(8); PG8_WAIT_L(0); PG8_BAR; PG8_MMA(1, 0, At, B0); PG8_MMA(1, 1, At, B1); PG8_BAR; PG8_SCHED;
;             PG8_LDB(B0, 1, 0); PG8_LDB(B1, 1, 1); PG8_SCHED; PG8_LDA(At, 1, 0); PG8_STAGE(PG8_SA(0, 1), a2 + hstepA, voffA);
;             PG8_WAIT_V(8); PG8_WAIT_L(0); PG8_BAR; PG8_MMA(0, 0, At, B0); PG8_MMA(0, 1, At, B1); PG8_BAR; PG8_SCHED;
;             PG8_LDA(At, 1, 1); PG8_STAGE(PG8_SB(1, 0), b3, voffB); PG8_STAGE(PG8_SB(1, 1), b3 + hstepB, voffB); PG8_STAGE(PG8_SA(1, 0), a3, voffA);
;             PG8_WAIT_V(8); PG8_WAIT_L(0); PG8_BAR; PG8_MMA(1, 0, At, B0); PG8_MMA(1, 1, At, B1); PG8_BAR; PG8_SCHED;
;         }
	s_add_i32 s34, s38, s41
	v_lshl_add_u64 v[160:161], v[160:161], 0, s[78:79]
	s_mov_b32 m0, s34
	ds_read_b128 v[178:181], v164 offset:49152
	ds_read_b128 v[182:185], v164 offset:50176
	ds_read_b128 v[186:189], v164 offset:51200
	ds_read_b128 v[190:193], v164 offset:52224
	ds_read_b128 v[200:203], v164 offset:53248
	ds_read_b128 v[204:207], v164 offset:54272
	ds_read_b128 v[208:211], v164 offset:55296
	ds_read_b128 v[212:215], v164 offset:56320
	global_load_lds_dwordx4 v[160:161], off
	s_add_i32 m0, s34, 0x2000
	s_add_u32 s30, s30, 0x20080
	v_lshl_add_u64 v[160:161], v[216:217], 0, s[78:79]
	s_addc_u32 s31, s31, 0
	s_add_i32 s34, s39, s41
	global_load_lds_dwordx4 v[160:161], off
	v_lshl_add_u64 v[160:161], s[30:31], 0, v[146:147]
	s_mov_b32 m0, s34
	s_nop 0
	global_load_lds_dwordx4 v[160:161], off
	v_lshl_add_u64 v[160:161], s[30:31], 0, v[150:151]
	s_add_i32 m0, s34, 0x2000
	s_nop 0
	global_load_lds_dwordx4 v[160:161], off
	v_lshl_add_u64 v[160:161], v[218:219], 0, s[78:79]
	s_mov_b32 m0, s49
	s_nop 0
	global_load_lds_dwordx4 v[160:161], off
	v_lshl_add_u64 v[160:161], v[220:221], 0, s[78:79]
	s_mov_b32 m0, s50
	s_nop 0
	global_load_lds_dwordx4 v[160:161], off
	s_waitcnt vmcnt(8)
	s_waitcnt lgkmcnt(0)
	s_barrier
	s_setprio 1
	s_waitcnt lgkmcnt(0)
	v_mfma_f32_16x16x32_bf16 v[60:63], v[128:131], v[178:181], v[60:63]
	v_mfma_f32_16x16x32_bf16 v[56:59], v[136:139], v[178:181], v[56:59]
	v_mfma_f32_16x16x32_bf16 v[44:47], v[128:131], v[186:189], v[44:47]
	v_mfma_f32_16x16x32_bf16 v[40:43], v[136:139], v[186:189], v[40:43]
	v_mfma_f32_16x16x32_bf16 v[28:31], v[128:131], v[200:203], v[28:31]
	v_mfma_f32_16x16x32_bf16 v[24:27], v[136:139], v[200:203], v[24:27]
	v_mfma_f32_16x16x32_bf16 v[12:15], v[128:131], v[208:211], v[12:15]
	v_mfma_f32_16x16x32_bf16 v[8:11], v[136:139], v[208:211], v[8:11]
	v_mfma_f32_16x16x32_bf16 v[60:63], v[132:135], v[182:185], v[60:63]
	v_mfma_f32_16x16x32_bf16 v[56:59], v[140:143], v[182:185], v[56:59]
	v_mfma_f32_16x16x32_bf16 v[44:47], v[132:135], v[190:193], v[44:47]
	v_mfma_f32_16x16x32_bf16 v[40:43], v[140:143], v[190:193], v[40:43]
	v_mfma_f32_16x16x32_bf16 v[28:31], v[132:135], v[204:207], v[28:31]
	v_mfma_f32_16x16x32_bf16 v[24:27], v[140:143], v[204:207], v[24:27]
	v_mfma_f32_16x16x32_bf16 v[12:15], v[132:135], v[212:215], v[12:15]
	v_mfma_f32_16x16x32_bf16 v[8:11], v[140:143], v[212:215], v[8:11]
	s_setprio 0
	s_setprio 1
	v_mfma_f32_16x16x32_bf16 v[52:55], v[156:159], v[178:181], v[52:55]
	v_mfma_f32_16x16x32_bf16 v[48:51], v[170:173], v[178:181], v[48:51]
	v_mfma_f32_16x16x32_bf16 v[36:39], v[156:159], v[186:189], v[36:39]
	v_mfma_f32_16x16x32_bf16 v[32:35], v[170:173], v[186:189], v[32:35]
	v_mfma_f32_16x16x32_bf16 v[20:23], v[156:159], v[200:203], v[20:23]
	v_mfma_f32_16x16x32_bf16 v[16:19], v[170:173], v[200:203], v[16:19]
	v_mfma_f32_16x16x32_bf16 v[4:7], v[156:159], v[208:211], v[4:7]
	v_mfma_f32_16x16x32_bf16 v[0:3], v[170:173], v[208:211], v[0:3]
	v_mfma_f32_16x16x32_bf16 v[52:55], v[166:169], v[182:185], v[52:55]
	v_mfma_f32_16x16x32_bf16 v[48:51], v[174:177], v[182:185], v[48:51]
	v_mfma_f32_16x16x32_bf16 v[36:39], v[166:169], v[190:193], v[36:39]
	v_mfma_f32_16x16x32_bf16 v[32:35], v[174:177], v[190:193], v[32:35]
	v_mfma_f32_16x16x32_bf16 v[20:23], v[166:169], v[204:207], v[20:23]
	v_mfma_f32_16x16x32_bf16 v[16:19], v[174:177], v[204:207], v[16:19]
	v_mfma_f32_16x16x32_bf16 v[4:7], v[166:169], v[212:215], v[4:7]
	v_mfma_f32_16x16x32_bf16 v[0:3], v[174:177], v[212:215], v[0:3]
	s_setprio 0
	s_add_i32 s37, s37, 2
	s_add_u32 s28, s28, 0x100
	s_addc_u32 s29, s29, 0
	s_add_u32 s33, s33, 0x100
	s_addc_u32 s36, s36, 0
	s_cmp_gt_u32 s37, 29
	s_cbranch_scc1 .Lp2_ktop_noh
	s_add_u32 s30, s28, 0xfff80080
	s_addc_u32 s31, s29, -1
	s_add_i32 s38, 0, 0x10000
	s_cmp_eq_u32 s37, 28
	s_cselect_b32 s35, s3, s31
	s_cselect_b32 s34, s21, s30
	s_cselect_b32 s31, s23, s36
	s_cselect_b32 s30, s27, s33
	s_add_i32 s59, 0, 0x14000
.Lp2_ktop_noh:
	s_cmp_gt_u32 s37, 29
	s_barrier
	s_cbranch_scc0 .Lp2_ktop
	s_and_b64 vcc, exec, s[14:15]
	s_cbranch_vccz .LBB0_225
	s_barrier

; #define PG8_STAGE(bufoff, gbase, voff) do { _Pragma("unroll") for (int _i = 0; _i < 2; ++_i) \
;         __builtin_amdgcn_global_load_lds((const unsigned*)((const char*)(gbase) + (voff)[_i]), (LAS unsigned*)(lds + (bufoff) + ldsw + _i * 8192), 16, 0, 0); } while (0)
; #define PG8_LDA(dst, b, h) do { _Pragma("unroll") for (int m = 0; m < 4; ++m) _Pragma("unroll") for (int k = 0; k < 2; ++k) dst[m][k] = *(const LAS bf16x8*)(lds + PG8_SA(b, h) + aoff + m * 2048 + k * 1024); } while (0)
; #define PG8_LDB(dst, b, h) do { _Pragma("unroll") for (int n = 0; n < 2; ++n) _Pragma("unroll") for (int k = 0; k < 2; ++k) dst[n][k] = *(const LAS bf16x8*)(lds + PG8_SB(b, h) + boff + n * 2048 + k * 1024); } while (0)
; #define PG8_MMA(ai, bj, At, Bt) do { __builtin_amdgcn_s_setprio(1); _Pragma("unroll") for (int m = 0; m < 4; ++m) _Pragma("unroll") for (int n = 0; n < 2; ++n) _Pragma("unroll") for (int k = 0; k < 2; ++k) \
;         acc[ai][bj][m][n] = __builtin_amdgcn_mfma_f32_16x16x32_bf16(Bt[n][k], At[m][k], acc[ai][bj][m][n], 0, 0, 0); __builtin_amdgcn_s_setprio(0); } while (0)
; #define PG8_WAIT_V(n) asm volatile("s_waitcnt vmcnt(" #n ")" ::: "memory")
; #define PG8_WAIT_L(n) asm volatile("s_waitcnt lgkmcnt(" #n ")" ::: "memory")
; #define PG8_BAR __builtin_amdgcn_s_barrier()
; #define PG8_SCHED __builtin_amdgcn_sched_barrier(0)
; template <class Epi, class Sched>
; __device__ __forceinline__ void gemm_stream(LAS unsigned char* lds, const int lda, const int ldb, const Sched& S, const Epi& E, const int wv) {
;     ...
;         for (int t = 0; t < nt; t += 2) {
;             const bool last = (t == nt - 2);
;             const char* a1 = cA + (size_t)(t + 1) * kstep;
;             const char* a2 = last ? nA : cA + (size_t)(t + 2) * kstep; const char* b2 = last ? nB : cB + (size_t)(t + 2) * kstep;
;             const char* a3 = a2 + kstep; const char* b3 = b2 + kstep;
;             PG8_LDB(B0, 0, 0); PG8_LDB(B1, 0, 1); PG8_SCHED; PG8_LDA(At, 0, 0); PG8_STAGE(PG8_SA(1, 1), a1 + hstepA, voffA);
;             PG8_WAIT_V(8); PG8_WAIT_L(0); PG8_BAR; PG8_MMA(0, 0, At, B0); PG8_MMA(0, 1, At, B1); PG8_BAR; PG8_SCHED;
;             PG8_LDA(At, 0, 1); PG8_STAGE(PG8_SB(0, 0), b2, voffB); PG8_STAGE(PG8_SB(0, 1), b2 + hstepB, voffB); PG8_STAGE(PG8_SA(0, 0), a2, voffA);
;             PG8_WAIT_V(8); PG8_WAIT_L(0); PG8_BAR; PG8_MMA(1, 0, At, B0); PG8_MMA(1, 1, At, B1); PG8_BAR; PG8_SCHED;
.Lp5_ktop:
	v_add_u32_e32 v140, s47, v165
	v_add_u32_e32 v167, s50, v165
	ds_read_b128 v[128:131], v140
	ds_read_b128 v[132:135], v140 offset:1024
	ds_read_b128 v[136:139], v140 offset:2048
	ds_read_b128 v[140:143], v140 offset:3072
	ds_read_b128 v[156:159], v167
	ds_read_b128 v[160:163], v167 offset:1024
	ds_read_b128 v[168:171], v167 offset:2048
	ds_read_b128 v[172:175], v167 offset:3072
	v_lshl_add_u64 v[192:193], s[20:21], 0, v[152:153]
	s_add_i32 m0, s31, 0xc000
	ds_read_b128 v[176:179], v166
	ds_read_b128 v[180:183], v166 offset:1024
	ds_read_b128 v[184:187], v166 offset:2048
	ds_read_b128 v[188:191], v166 offset:3072
	ds_read_b128 v[200:203], v166 offset:4096
	ds_read_b128 v[204:207], v166 offset:5120
	ds_read_b128 v[208:211], v166 offset:6144
	ds_read_b128 v[212:215], v166 offset:7168
	global_load_lds_dwordx4 v[192:193], off
	v_lshl_add_u64 v[192:193], s[20:21], 0, v[154:155]
	s_add_i32 m0, s31, 0xe000
	s_nop 0
	global_load_lds_dwordx4 v[192:193], off
	s_waitcnt vmcnt(8)
	s_waitcnt lgkmcnt(0)
	s_barrier
	s_setprio 1
	s_waitcnt lgkmcnt(0)
	v_mfma_f32_16x16x32_bf16 v[124:127], v[128:131], v[176:179], v[124:127]
	v_mfma_f32_16x16x32_bf16 v[120:123], v[136:139], v[176:179], v[120:123]
	v_mfma_f32_16x16x32_bf16 v[108:111], v[128:131], v[184:187], v[108:111]
	v_mfma_f32_16x16x32_bf16 v[104:107], v[136:139], v[184:187], v[104:107]
	v_mfma_f32_16x16x32_bf16 v[92:95], v[128:131], v[200:203], v[92:95]
	v_mfma_f32_16x16x32_bf16 v[88:91], v[136:139], v[200:203], v[88:91]
	v_mfma_f32_16x16x32_bf16 v[76:79], v[128:131], v[208:211], v[76:79]
	v_mfma_f32_16x16x32_bf16 v[72:75], v[136:139], v[208:211], v[72:75]
	v_mfma_f32_16x16x32_bf16 v[124:127], v[132:135], v[180:183], v[124:127]
	v_mfma_f32_16x16x32_bf16 v[120:123], v[140:143], v[180:183], v[120:123]
	v_mfma_f32_16x16x32_bf16 v[108:111], v[132:135], v[188:191], v[108:111]
	v_mfma_f32_16x16x32_bf16 v[104:107], v[140:143], v[188:191], v[104:107]
	v_mfma_f32_16x16x32_bf16 v[92:95], v[132:135], v[204:207], v[92:95]
	v_mfma_f32_16x16x32_bf16 v[88:91], v[140:143], v[204:207], v[88:91]
	v_mfma_f32_16x16x32_bf16 v[76:79], v[132:135], v[212:215], v[76:79]
	v_mfma_f32_16x16x32_bf16 v[72:75], v[140:143], v[212:215], v[72:75]
	s_setprio 0
	s_setprio 1
	v_mfma_f32_16x16x32_bf16 v[116:119], v[156:159], v[176:179], v[116:119]
	v_mfma_f32_16x16x32_bf16 v[112:115], v[168:171], v[176:179], v[112:115]
	v_mfma_f32_16x16x32_bf16 v[100:103], v[156:159], v[184:187], v[100:103]
	v_mfma_f32_16x16x32_bf16 v[96:99], v[168:171], v[184:187], v[96:99]
	v_mfma_f32_16x16x32_bf16 v[84:87], v[156:159], v[200:203], v[84:87]
	v_mfma_f32_16x16x32_bf16 v[80:83], v[168:171], v[200:203], v[80:83]
	v_mfma_f32_16x16x32_bf16 v[68:71], v[156:159], v[208:211], v[68:71]
	v_mfma_f32_16x16x32_bf16 v[64:67], v[168:171], v[208:211], v[64:67]
	v_mfma_f32_16x16x32_bf16 v[116:119], v[160:163], v[180:183], v[116:119]
	v_mfma_f32_16x16x32_bf16 v[112:115], v[172:175], v[180:183], v[112:115]
	v_mfma_f32_16x16x32_bf16 v[100:103], v[160:163], v[188:191], v[100:103]
	v_mfma_f32_16x16x32_bf16 v[96:99], v[172:175], v[188:191], v[96:99]
	v_mfma_f32_16x16x32_bf16 v[84:87], v[160:163], v[204:207], v[84:87]
	v_mfma_f32_16x16x32_bf16 v[80:83], v[172:175], v[204:207], v[80:83]
	v_mfma_f32_16x16x32_bf16 v[68:71], v[160:163], v[212:215], v[68:71]
	v_mfma_f32_16x16x32_bf16 v[64:67], v[172:175], v[212:215], v[64:67]
	s_setprio 0
	s_barrier
	s_add_i32 s47, s47, s30
	v_lshl_add_u64 v[192:193], s[22:23], 0, v[148:149]
	s_mov_b32 m0, s47
	ds_read_b128 v[176:179], v166 offset:16384
	ds_read_b128 v[180:183], v166 offset:17408
	ds_read_b128 v[184:187], v166 offset:18432
	ds_read_b128 v[188:191], v166 offset:19456
	ds_read_b128 v[200:203], v166 offset:20480
	ds_read_b128 v[204:207], v166 offset:21504
	ds_read_b128 v[208:211], v166 offset:22528
	ds_read_b128 v[212:215], v166 offset:23552
	global_load_lds_dwordx4 v[192:193], off
	s_add_i32 m0, s47, 0x2000
	s_add_u32 s48, s22, 0x20000
	v_lshl_add_u64 v[196:197], s[22:23], 0, v[144:145]
	s_addc_u32 s49, s23, 0
	s_add_i32 s47, s50, s30
	global_load_lds_dwordx4 v[196:197], off
	v_lshl_add_u64 v[198:199], s[48:49], 0, v[148:149]
	s_mov_b32 m0, s47
	v_lshl_add_u64 v[216:217], s[24:25], 0, v[146:147]
	global_load_lds_dwordx4 v[198:199], off
	v_lshl_add_u64 v[198:199], s[48:49], 0, v[144:145]
	s_add_i32 m0, s47, 0x2000
	s_nop 0
	global_load_lds_dwordx4 v[198:199], off
	v_lshl_add_u64 v[198:199], s[24:25], 0, v[150:151]
	s_mov_b32 m0, s31
	s_nop 0
	global_load_lds_dwordx4 v[198:199], off
	s_mov_b32 m0, s34
	s_nop 0
	global_load_lds_dwordx4 v[216:217], off
	s_waitcnt vmcnt(8)
	s_waitcnt lgkmcnt(0)
	s_barrier
; #define PG8_STAGE(bufoff, gbase, voff) do { _Pragma("unroll") for (int _i = 0; _i < 2; ++_i) \
;         __builtin_amdgcn_global_load_lds((const unsigned*)((const char*)(gbase) + (voff)[_i]), (LAS unsigned*)(lds + (bufoff) + ldsw + _i * 8192), 16, 0, 0); } while (0)
; #define PG8_LDA(dst, b, h) do { _Pragma("unroll") for (int m = 0; m < 4; ++m) _Pragma("unroll") for (int k = 0; k < 2; ++k) dst[m][k] = *(const LAS bf16x8*)(lds + PG8_SA(b, h) + aoff + m * 2048 + k * 1024); } while (0)
; #define PG8_LDB(dst, b, h) do { _Pragma("unroll") for (int n = 0; n < 2; ++n) _Pragma("unroll") for (int k = 0; k < 2; ++k) dst[n][k] = *(const LAS bf16x8*)(lds + PG8_SB(b, h) + boff + n * 2048 + k * 1024); } while (0)
; #define PG8_MMA(ai, bj, At, Bt) do { __builtin_amdgcn_s_setprio(1); _Pragma("unroll") for (int m = 0; m < 4; ++m) _Pragma("unroll") for (int n = 0; n < 2; ++n) _Pragma("unroll") for (int k = 0; k < 2; ++k) \
;         acc[ai][bj][m][n] = __builtin_amdgcn_mfma_f32_16x16x32_bf16(Bt[n][k], At[m][k], acc[ai][bj][m][n], 0, 0, 0); __builtin_amdgcn_s_setprio(0); } while (0)
; #define PG8_WAIT_V(n) asm volatile("s_waitcnt vmcnt(" #n ")" ::: "memory")
; #define PG8_WAIT_L(n) asm volatile("s_waitcnt lgkmcnt(" #n ")" ::: "memory")
; #define PG8_BAR __builtin_amdgcn_s_barrier()
; #define PG8_SCHED __builtin_amdgcn_sched_barrier(0)
; template <class Epi, class Sched>
; __device__ __forceinline__ void gemm_stream(LAS unsigned char* lds, const int lda, const int ldb, const Sched& S, const Epi& E, const int wv) {
;     ...
;             PG8_LDA(At, 0, 1); PG8_STAGE(PG8_SB(0, 0), b2, voffB); PG8_STAGE(PG8_SB(0, 1), b2 + hstepB, voffB); PG8_STAGE(PG8_SA(0, 0), a2, voffA);
;             PG8_WAIT_V(8); PG8_WAIT_L(0); PG8_BAR; PG8_MMA(1, 0, At, B0); PG8_MMA(1, 1, At, B1); PG8_BAR; PG8_SCHED;
;             PG8_LDB(B0, 1, 0); PG8_LDB(B1, 1, 1); PG8_SCHED; PG8_LDA(At, 1, 0); PG8_STAGE(PG8_SA(0, 1), a2 + hstepA, voffA);
;             PG8_WAIT_V(8); PG8_WAIT_L(0); PG8_BAR; PG8_MMA(0, 0, At, B0); PG8_MMA(0, 1, At, B1); PG8_BAR; PG8_SCHED;
	s_setprio 1
	s_waitcnt lgkmcnt(0)
	v_mfma_f32_16x16x32_bf16 v[60:63], v[128:131], v[176:179], v[60:63]
	v_mfma_f32_16x16x32_bf16 v[56:59], v[136:139], v[176:179], v[56:59]
	v_mfma_f32_16x16x32_bf16 v[44:47], v[128:131], v[184:187], v[44:47]
	v_mfma_f32_16x16x32_bf16 v[40:43], v[136:139], v[184:187], v[40:43]
	v_mfma_f32_16x16x32_bf16 v[28:31], v[128:131], v[200:203], v[28:31]
	v_mfma_f32_16x16x32_bf16 v[24:27], v[136:139], v[200:203], v[24:27]
	v_mfma_f32_16x16x32_bf16 v[12:15], v[128:131], v[208:211], v[12:15]
	v_mfma_f32_16x16x32_bf16 v[8:11], v[136:139], v[208:211], v[8:11]
	v_mfma_f32_16x16x32_bf16 v[60:63], v[132:135], v[180:183], v[60:63]
	v_mfma_f32_16x16x32_bf16 v[56:59], v[140:143], v[180:183], v[56:59]
	v_mfma_f32_16x16x32_bf16 v[44:47], v[132:135], v[188:191], v[44:47]
	v_mfma_f32_16x16x32_bf16 v[40:43], v[140:143], v[188:191], v[40:43]
	v_mfma_f32_16x16x32_bf16 v[28:31], v[132:135], v[204:207], v[28:31]
	v_mfma_f32_16x16x32_bf16 v[24:27], v[140:143], v[204:207], v[24:27]
	v_mfma_f32_16x16x32_bf16 v[12:15], v[132:135], v[212:215], v[12:15]
	v_mfma_f32_16x16x32_bf16 v[8:11], v[140:143], v[212:215], v[8:11]
	s_setprio 0
	s_setprio 1
	v_mfma_f32_16x16x32_bf16 v[52:55], v[156:159], v[176:179], v[52:55]
	v_mfma_f32_16x16x32_bf16 v[48:51], v[168:171], v[176:179], v[48:51]
	v_mfma_f32_16x16x32_bf16 v[36:39], v[156:159], v[184:187], v[36:39]
	v_mfma_f32_16x16x32_bf16 v[32:35], v[168:171], v[184:187], v[32:35]
	v_mfma_f32_16x16x32_bf16 v[20:23], v[156:159], v[200:203], v[20:23]
	v_mfma_f32_16x16x32_bf16 v[16:19], v[168:171], v[200:203], v[16:19]
	v_mfma_f32_16x16x32_bf16 v[4:7], v[156:159], v[208:211], v[4:7]
	v_mfma_f32_16x16x32_bf16 v[0:3], v[168:171], v[208:211], v[0:3]
	v_mfma_f32_16x16x32_bf16 v[52:55], v[160:163], v[180:183], v[52:55]
	v_mfma_f32_16x16x32_bf16 v[48:51], v[172:175], v[180:183], v[48:51]
	v_mfma_f32_16x16x32_bf16 v[36:39], v[160:163], v[188:191], v[36:39]
	v_mfma_f32_16x16x32_bf16 v[32:35], v[172:175], v[188:191], v[32:35]
	v_mfma_f32_16x16x32_bf16 v[20:23], v[160:163], v[204:207], v[20:23]
	v_mfma_f32_16x16x32_bf16 v[16:19], v[172:175], v[204:207], v[16:19]
	v_mfma_f32_16x16x32_bf16 v[4:7], v[160:163], v[212:215], v[4:7]
	v_mfma_f32_16x16x32_bf16 v[0:3], v[172:175], v[212:215], v[0:3]
	s_setprio 0
	s_barrier
	s_add_i32 s47, 0, 0x18000
	s_add_i32 s48, 0, 0x1c000
	v_add_u32_e32 v140, s47, v165
	v_add_u32_e32 v167, s48, v165
	ds_read_b128 v[128:131], v140
	ds_read_b128 v[132:135], v140 offset:1024
	ds_read_b128 v[136:139], v140 offset:2048
	ds_read_b128 v[140:143], v140 offset:3072
	ds_read_b128 v[156:159], v167
	ds_read_b128 v[160:163], v167 offset:1024
	ds_read_b128 v[168:171], v167 offset:2048
	ds_read_b128 v[172:175], v167 offset:3072
	s_add_u32 s24, s24, 0x80000
	s_addc_u32 s25, s25, 0
	s_mov_b32 m0, s35
	v_lshl_add_u64 v[218:219], s[24:25], 0, v[150:151]
	ds_read_b128 v[176:179], v166 offset:32768
	ds_read_b128 v[180:183], v166 offset:33792
	ds_read_b128 v[184:187], v166 offset:34816
	ds_read_b128 v[188:191], v166 offset:35840
	ds_read_b128 v[200:203], v166 offset:36864
	ds_read_b128 v[204:207], v166 offset:37888
	ds_read_b128 v[208:211], v166 offset:38912
	ds_read_b128 v[212:215], v166 offset:39936
	global_load_lds_dwordx4 v[218:219], off
	v_lshl_add_u64 v[218:219], s[24:25], 0, v[146:147]
	s_mov_b32 m0, s36
	s_nop 0
	global_load_lds_dwordx4 v[218:219], off
	s_waitcnt vmcnt(8)
	s_waitcnt lgkmcnt(0)
	s_barrier
	s_setprio 1
	s_waitcnt lgkmcnt(0)
	v_mfma_f32_16x16x32_bf16 v[124:127], v[128:131], v[176:179], v[124:127]
	v_mfma_f32_16x16x32_bf16 v[120:123], v[136:139], v[176:179], v[120:123]
	v_mfma_f32_16x16x32_bf16 v[108:111], v[128:131], v[184:187], v[108:111]
	v_mfma_f32_16x16x32_bf16 v[104:107], v[136:139], v[184:187], v[104:107]
	v_mfma_f32_16x16x32_bf16 v[92:95], v[128:131], v[200:203], v[92:95]
	v_mfma_f32_16x16x32_bf16 v[88:91], v[136:139], v[200:203], v[88:91]
	v_mfma_f32_16x16x32_bf16 v[76:79], v[128:131], v[208:211], v[76:79]
	v_mfma_f32_16x16x32_bf16 v[72:75], v[136:139], v[208:211], v[72:75]
	v_mfma_f32_16x16x32_bf16 v[124:127], v[132:135], v[180:183], v[124:127]
	v_mfma_f32_16x16x32_bf16 v[120:123], v[140:143], v[180:183], v[120:123]
	v_mfma_f32_16x16x32_bf16 v[108:111], v[132:135], v[188:191], v[108:111]
	v_mfma_f32_16x16x32_bf16 v[104:107], v[140:143], v[188:191], v[104:107]
	v_mfma_f32_16x16x32_bf16 v[92:95], v[132:135], v[204:207], v[92:95]
	v_mfma_f32_16x16x32_bf16 v[88:91], v[140:143], v[204:207], v[88:91]
	v_mfma_f32_16x16x32_bf16 v[76:79], v[132:135], v[212:215], v[76:79]
	v_mfma_f32_16x16x32_bf16 v[72:75], v[140:143], v[212:215], v[72:75]
	s_setprio 0
	s_setprio 1
	v_mfma_f32_16x16x32_bf16 v[116:119], v[156:159], v[176:179], v[116:119]
	v_mfma_f32_16x16x32_bf16 v[112:115], v[168:171], v[176:179], v[112:115]
	v_mfma_f32_16x16x32_bf16 v[100:103], v[156:159], v[184:187], v[100:103]
	v_mfma_f32_16x16x32_bf16 v[96:99], v[168:171], v[184:187], v[96:99]
	v_mfma_f32_16x16x32_bf16 v[84:87], v[156:159], v[200:203], v[84:87]
	v_mfma_f32_16x16x32_bf16 v[80:83], v[168:171], v[200:203], v[80:83]
	v_mfma_f32_16x16x32_bf16 v[68:71], v[156:159], v[208:211], v[68:71]
	v_mfma_f32_16x16x32_bf16 v[64:67], v[168:171], v[208:211], v[64:67]
	v_mfma_f32_16x16x32_bf16 v[116:119], v[160:163], v[180:183], v[116:119]
	v_mfma_f32_16x16x32_bf16 v[112:115], v[172:175], v[180:183], v[112:115]
	v_mfma_f32_16x16x32_bf16 v[100:103], v[160:163], v[188:191], v[100:103]
	v_mfma_f32_16x16x32_bf16 v[96:99], v[172:175], v[188:191], v[96:99]
	v_mfma_f32_16x16x32_bf16 v[84:87], v[160:163], v[204:207], v[84:87]
	v_mfma_f32_16x16x32_bf16 v[80:83], v[172:175], v[204:207], v[80:83]
	v_mfma_f32_16x16x32_bf16 v[68:71], v[160:163], v[212:215], v[68:71]
	v_mfma_f32_16x16x32_bf16 v[64:67], v[172:175], v[212:215], v[64:67]
	s_setprio 0
	s_barrier
; #define PG8_STAGE(bufoff, gbase, voff) do { _Pragma("unroll") for (int _i = 0; _i < 2; ++_i) \
;         __builtin_amdgcn_global_load_lds((const unsigned*)((const char*)(gbase) + (voff)[_i]), (LAS unsigned*)(lds + (bufoff) + ldsw + _i * 8192), 16, 0, 0); } while (0)
; #define PG8_LDA(dst, b, h) do { _Pragma("unroll") for (int m = 0; m < 4; ++m) _Pragma("unroll") for (int k = 0; k < 2; ++k) dst[m][k] = *(const LAS bf16x8*)(lds + PG8_SA(b, h) + aoff + m * 2048 + k * 1024); } while (0)
; #define PG8_LDB(dst, b, h) do { _Pragma("unroll") for (int n = 0; n < 2; ++n) _Pragma("unroll") for (int k = 0; k < 2; ++k) dst[n][k] = *(const LAS bf16x8*)(lds + PG8_SB(b, h) + boff + n * 2048 + k * 1024); } while (0)
; #define PG8_WAIT_V(n) asm volatile("s_waitcnt vmcnt(" #n ")" ::: "memory")
; template <class Epi, class Sched>
; __device__ __forceinline__ void gemm_stream(LAS unsigned char* lds, const int lda, const int ldb, const Sched& S, const Epi& E, const int wv) {
;     ...
;         for (int t = 0; t < nt; t += 2) {
;             const bool last = (t == nt - 2);
;             const char* a1 = cA + (size_t)(t + 1) * kstep;
;             const char* a2 = last ? nA : cA + (size_t)(t + 2) * kstep; const char* b2 = last ? nB : cB + (size_t)(t + 2) * kstep;
;             const char* a3 = a2 + kstep; const char* b3 = b2 + kstep;
;             PG8_LDB(B0, 0, 0); PG8_LDB(B1, 0, 1); PG8_SCHED; PG8_LDA(At, 0, 0); PG8_STAGE(PG8_SA(1, 1), a1 + hstepA, voffA);
;             PG8_WAIT_V(8); PG8_WAIT_L(0); PG8_BAR; PG8_MMA(0, 0, At, B0); PG8_MMA(0, 1, At, B1); PG8_BAR; PG8_SCHED;
;             PG8_LDA(At, 0, 1); PG8_STAGE(PG8_SB(0, 0), b2, voffB); PG8_STAGE(PG8_SB(0, 1), b2 + hstepB, voffB); PG8_STAGE(PG8_SA(0, 0), a2, voffA);
;             PG8_WAIT_V(8); PG8_WAIT_L(0); PG8_BAR; PG8_MMA(1, 0, At, B0); PG8_MMA(1, 1, At, B1); PG8_BAR; PG8_SCHED;
;             PG8_LDB(B0, 1, 0); PG8_LDB(B1, 1, 1); PG8_SCHED; PG8_LDA(At, 1, 0); PG8_STAGE(PG8_SA(0, 1), a2 + hstepA, voffA);
;             PG8_WAIT_V(8); PG8_WAIT_L(0); PG8_BAR; PG8_MMA(0, 0, At, B0); PG8_MMA(0, 1, At, B1); PG8_BAR; PG8_SCHED;
;             PG8_LDA(At, 1, 1); PG8_STAGE(PG8_SB(1, 0), b3, voffB); PG8_STAGE(PG8_SB(1, 1), b3 + hstepB, voffB); PG8_STAGE(PG8_SA(1, 0), a3, voffA);
;             PG8_WAIT_V(8); PG8_WAIT_L(0); PG8_BAR; PG8_MMA(1, 0, At, B0); PG8_MMA(1, 1, At, B1); PG8_BAR; PG8_SCHED;
;         }
	s_add_i32 s24, s47, s30
	v_lshl_add_u64 v[192:193], v[192:193], 0, s[78:79]
	s_mov_b32 m0, s24
	ds_read_b128 v[176:179], v166 offset:49152
	ds_read_b128 v[180:183], v166 offset:50176
	ds_read_b128 v[184:187], v166 offset:51200
	ds_read_b128 v[188:191], v166 offset:52224
	ds_read_b128 v[200:203], v166 offset:53248
	ds_read_b128 v[204:207], v166 offset:54272
	ds_read_b128 v[208:211], v166 offset:55296
	ds_read_b128 v[212:215], v166 offset:56320
	global_load_lds_dwordx4 v[192:193], off
	s_add_i32 m0, s24, 0x2000
	s_add_u32 s22, s22, 0x20080
	v_lshl_add_u64 v[192:193], v[196:197], 0, s[78:79]
	s_addc_u32 s23, s23, 0
	s_add_i32 s24, s48, s30
	global_load_lds_dwordx4 v[192:193], off
	v_lshl_add_u64 v[192:193], s[22:23], 0, v[148:149]
	s_mov_b32 m0, s24
	s_nop 0
	global_load_lds_dwordx4 v[192:193], off
	v_lshl_add_u64 v[192:193], s[22:23], 0, v[144:145]
	s_add_i32 m0, s24, 0x2000
	s_nop 0
	global_load_lds_dwordx4 v[192:193], off
	v_lshl_add_u64 v[192:193], v[198:199], 0, s[78:79]
	s_mov_b32 m0, s40
	s_nop 0
	global_load_lds_dwordx4 v[192:193], off
	v_lshl_add_u64 v[192:193], v[216:217], 0, s[78:79]
	s_mov_b32 m0, s41
	s_nop 0
	global_load_lds_dwordx4 v[192:193], off
	s_waitcnt vmcnt(8)
	s_waitcnt lgkmcnt(0)
	s_barrier
	s_setprio 1
	s_waitcnt lgkmcnt(0)
	v_mfma_f32_16x16x32_bf16 v[60:63], v[128:131], v[176:179], v[60:63]
	v_mfma_f32_16x16x32_bf16 v[56:59], v[136:139], v[176:179], v[56:59]
	v_mfma_f32_16x16x32_bf16 v[44:47], v[128:131], v[184:187], v[44:47]
	v_mfma_f32_16x16x32_bf16 v[40:43], v[136:139], v[184:187], v[40:43]
	v_mfma_f32_16x16x32_bf16 v[28:31], v[128:131], v[200:203], v[28:31]
	v_mfma_f32_16x16x32_bf16 v[24:27], v[136:139], v[200:203], v[24:27]
	v_mfma_f32_16x16x32_bf16 v[12:15], v[128:131], v[208:211], v[12:15]
	v_mfma_f32_16x16x32_bf16 v[8:11], v[136:139], v[208:211], v[8:11]
	v_mfma_f32_16x16x32_bf16 v[60:63], v[132:135], v[180:183], v[60:63]
	v_mfma_f32_16x16x32_bf16 v[56:59], v[140:143], v[180:183], v[56:59]
	v_mfma_f32_16x16x32_bf16 v[44:47], v[132:135], v[188:191], v[44:47]
	v_mfma_f32_16x16x32_bf16 v[40:43], v[140:143], v[188:191], v[40:43]
	v_mfma_f32_16x16x32_bf16 v[28:31], v[132:135], v[204:207], v[28:31]
	v_mfma_f32_16x16x32_bf16 v[24:27], v[140:143], v[204:207], v[24:27]
	v_mfma_f32_16x16x32_bf16 v[12:15], v[132:135], v[212:215], v[12:15]
	v_mfma_f32_16x16x32_bf16 v[8:11], v[140:143], v[212:215], v[8:11]
	s_setprio 0
	s_setprio 1
	v_mfma_f32_16x16x32_bf16 v[52:55], v[156:159], v[176:179], v[52:55]
	v_mfma_f32_16x16x32_bf16 v[48:51], v[168:171], v[176:179], v[48:51]
	v_mfma_f32_16x16x32_bf16 v[36:39], v[156:159], v[184:187], v[36:39]
	v_mfma_f32_16x16x32_bf16 v[32:35], v[168:171], v[184:187], v[32:35]
	v_mfma_f32_16x16x32_bf16 v[20:23], v[156:159], v[200:203], v[20:23]
	v_mfma_f32_16x16x32_bf16 v[16:19], v[168:171], v[200:203], v[16:19]
	v_mfma_f32_16x16x32_bf16 v[4:7], v[156:159], v[208:211], v[4:7]
	v_mfma_f32_16x16x32_bf16 v[0:3], v[168:171], v[208:211], v[0:3]
	v_mfma_f32_16x16x32_bf16 v[52:55], v[160:163], v[180:183], v[52:55]
	v_mfma_f32_16x16x32_bf16 v[48:51], v[172:175], v[180:183], v[48:51]
	v_mfma_f32_16x16x32_bf16 v[36:39], v[160:163], v[188:191], v[36:39]
	v_mfma_f32_16x16x32_bf16 v[32:35], v[172:175], v[188:191], v[32:35]
	v_mfma_f32_16x16x32_bf16 v[20:23], v[160:163], v[204:207], v[20:23]
	v_mfma_f32_16x16x32_bf16 v[16:19], v[172:175], v[204:207], v[16:19]
	v_mfma_f32_16x16x32_bf16 v[4:7], v[160:163], v[212:215], v[4:7]
	v_mfma_f32_16x16x32_bf16 v[0:3], v[172:175], v[212:215], v[0:3]
	s_setprio 0
	s_add_i32 s46, s46, 2
	s_add_u32 s20, s20, 0x100
	s_addc_u32 s21, s21, 0
	s_add_u32 s13, s13, 0x100
	s_addc_u32 s15, s15, 0
	s_cmp_gt_u32 s46, 29
	s_cbranch_scc1 .Lp5_ktop_noh
	s_add_u32 s22, s20, 0xfff80080
	s_addc_u32 s23, s21, -1
	s_add_i32 s47, 0, 0x10000
	s_cmp_eq_u32 s46, 28
	s_cselect_b32 s25, s17, s23
	s_cselect_b32 s24, s16, s22
	s_cselect_b32 s23, s19, s15
	s_cselect_b32 s22, s18, s13
	s_add_i32 s50, 0, 0x14000
.Lp5_ktop_noh:
	s_cmp_gt_u32 s46, 29
	s_barrier
	s_cbranch_scc0 .Lp5_ktop
	s_and_b64 vcc, exec, s[6:7]
	s_cbranch_vccz .LBB0_603
	s_barrier
